# phase-8 SiLU-gate tile epilogue: per-wave LDS-staged 16-byte stores with f32 rcp-based SiLU instead of eight masked blocks of scalar silu + 2-byte stores
# speedup vs baseline: 1.0332x; 1.0035x over previous
.LBB0_94:
	s_barrier
	s_cmp_eq_u32 s100, 1
	s_cbranch_scc1 .Lp9_after_gate
	s_add_i32 s5, s5, s64
	s_add_i32 s4, s4, s51
	s_cmpk_eq_i32 s64, 0x200
	s_cbranch_scc1 .LBB0_127
	s_cmpk_gt_i32 s5, 0x31f
	s_cbranch_scc1 .LBB0_127

.LBB0_103:
	v_readfirstlane_b32 s0, v189
	s_lshr_b32 s0, s0, 6
	s_and_b32 s0, s0, 1
	s_lshl_b32 s0, s0, 6
	s_add_i32 s0, s0, s6
	s_cmpk_gt_i32 s0, 0xc00
	s_cbranch_scc1 .Lg8_skip
	s_mov_b64 s[8:9], 0x8000
	v_and_b32_e32 v152, 63, v189
	v_lshrrev_b32_e32 v153, 6, v189
	v_and_b32_e32 v154, 31, v152
	v_lshrrev_b32_e32 v155, 5, v152
	v_lshrrev_b32_e32 v156, 3, v154
	v_and_b32_e32 v157, 7, v154
	v_lshlrev_b32_e32 v158, 14, v153
	v_lshl_add_u32 v159, v155, 9, v158
	v_lshl_add_u32 v159, v157, 1, v159
	v_lshl_add_u32 v160, v155, 2, v156
	v_xor_b32_e32 v161, 4, v160
	v_lshl_add_u32 v160, v160, 4, v159
	v_lshl_add_u32 v161, v161, 4, v159
	v_lshrrev_b32_e32 v162, 3, v152
	v_and_b32_e32 v163, 7, v152
	v_lshlrev_b32_e32 v164, 2, v155
	v_xor_b32_e32 v164, v163, v164
	v_lshl_add_u32 v165, v162, 7, v158
	v_lshl_add_u32 v166, v164, 4, v165
	v_lshrrev_b32_e32 v167, 1, v153
	v_lshl_add_u32 v167, v167, 7, v162
	v_add_u32_e32 v167, s7, v167
	v_and_b32_e32 v168, 1, v153
	v_lshl_add_u32 v168, v168, 6, s6
	v_lshl_add_u32 v168, v163, 3, v168
	v_lshlrev_b32_e32 v170, 12, v167
	v_lshl_add_u32 v170, v168, 1, v170
	v_add_u32_e32 v170, 0x5fff780, v170
	v_mov_b32_e32 v171, 0
	v_lshl_add_u64 v[170:171], s[14:15], 0, v[170:171]
	v_mul_f32_e32 v172, 0xbfb8aa3b, v112
	v_mul_f32_e32 v173, 0xbfb8aa3b, v113
	v_mul_f32_e32 v174, 0xbfb8aa3b, v114
	v_mul_f32_e32 v175, 0xbfb8aa3b, v115
	v_exp_f32_e32 v172, v172
	v_exp_f32_e32 v173, v173
	v_exp_f32_e32 v174, v174
	v_exp_f32_e32 v175, v175
	v_add_f32_e32 v172, 1.0, v172
	v_add_f32_e32 v173, 1.0, v173
	v_add_f32_e32 v174, 1.0, v174
	v_add_f32_e32 v175, 1.0, v175
	v_rcp_f32_e32 v172, v172
	v_rcp_f32_e32 v173, v173
	v_rcp_f32_e32 v174, v174
	v_rcp_f32_e32 v175, v175
	v_mul_f32_e32 v112, v112, v172
	v_mul_f32_e32 v113, v113, v173
	v_mul_f32_e32 v114, v114, v174
	v_mul_f32_e32 v115, v115, v175
	v_cvt_pk_bf16_f32 v112, v112, v113
	v_cvt_pk_bf16_f32 v114, v114, v115
	ds_write_b16 v160, v112 offset:0
	ds_write_b16_d16_hi v160, v112 offset:128
	ds_write_b16 v160, v114 offset:256
	ds_write_b16_d16_hi v160, v114 offset:384
	v_mul_f32_e32 v172, 0xbfb8aa3b, v116
	v_mul_f32_e32 v173, 0xbfb8aa3b, v117
	v_mul_f32_e32 v174, 0xbfb8aa3b, v118
	v_mul_f32_e32 v175, 0xbfb8aa3b, v119
	v_exp_f32_e32 v172, v172
	v_exp_f32_e32 v173, v173
	v_exp_f32_e32 v174, v174
	v_exp_f32_e32 v175, v175
	v_add_f32_e32 v172, 1.0, v172
	v_add_f32_e32 v173, 1.0, v173
	v_add_f32_e32 v174, 1.0, v174
	v_add_f32_e32 v175, 1.0, v175
	v_rcp_f32_e32 v172, v172
	v_rcp_f32_e32 v173, v173
	v_rcp_f32_e32 v174, v174
	v_rcp_f32_e32 v175, v175
	v_mul_f32_e32 v116, v116, v172
	v_mul_f32_e32 v117, v117, v173
	v_mul_f32_e32 v118, v118, v174
	v_mul_f32_e32 v119, v119, v175
	v_cvt_pk_bf16_f32 v116, v116, v117
	v_cvt_pk_bf16_f32 v118, v118, v119
	ds_write_b16 v160, v116 offset:1024
	ds_write_b16_d16_hi v160, v116 offset:1152
	ds_write_b16 v160, v118 offset:1280
	ds_write_b16_d16_hi v160, v118 offset:1408
	v_mul_f32_e32 v172, 0xbfb8aa3b, v120
	v_mul_f32_e32 v173, 0xbfb8aa3b, v121
	v_mul_f32_e32 v174, 0xbfb8aa3b, v122
	v_mul_f32_e32 v175, 0xbfb8aa3b, v123
	v_exp_f32_e32 v172, v172
	v_exp_f32_e32 v173, v173
	v_exp_f32_e32 v174, v174
	v_exp_f32_e32 v175, v175
	v_add_f32_e32 v172, 1.0, v172
	v_add_f32_e32 v173, 1.0, v173
	v_add_f32_e32 v174, 1.0, v174
	v_add_f32_e32 v175, 1.0, v175
	v_rcp_f32_e32 v172, v172
	v_rcp_f32_e32 v173, v173
	v_rcp_f32_e32 v174, v174
	v_rcp_f32_e32 v175, v175
	v_mul_f32_e32 v120, v120, v172
	v_mul_f32_e32 v121, v121, v173
	v_mul_f32_e32 v122, v122, v174
	v_mul_f32_e32 v123, v123, v175
	v_cvt_pk_bf16_f32 v120, v120, v121
	v_cvt_pk_bf16_f32 v122, v122, v123
	ds_write_b16 v160, v120 offset:2048
	ds_write_b16_d16_hi v160, v120 offset:2176
	ds_write_b16 v160, v122 offset:2304
	ds_write_b16_d16_hi v160, v122 offset:2432
	v_mul_f32_e32 v172, 0xbfb8aa3b, v124
	v_mul_f32_e32 v173, 0xbfb8aa3b, v125
	v_mul_f32_e32 v174, 0xbfb8aa3b, v126
	v_mul_f32_e32 v175, 0xbfb8aa3b, v127
	v_exp_f32_e32 v172, v172
	v_exp_f32_e32 v173, v173
	v_exp_f32_e32 v174, v174
	v_exp_f32_e32 v175, v175
	v_add_f32_e32 v172, 1.0, v172
	v_add_f32_e32 v173, 1.0, v173
	v_add_f32_e32 v174, 1.0, v174
	v_add_f32_e32 v175, 1.0, v175
	v_rcp_f32_e32 v172, v172
	v_rcp_f32_e32 v173, v173
	v_rcp_f32_e32 v174, v174
	v_rcp_f32_e32 v175, v175
	v_mul_f32_e32 v124, v124, v172
	v_mul_f32_e32 v125, v125, v173
	v_mul_f32_e32 v126, v126, v174
	v_mul_f32_e32 v127, v127, v175
	v_cvt_pk_bf16_f32 v124, v124, v125
	v_cvt_pk_bf16_f32 v126, v126, v127
	ds_write_b16 v160, v124 offset:3072
	ds_write_b16_d16_hi v160, v124 offset:3200
	ds_write_b16 v160, v126 offset:3328
	ds_write_b16_d16_hi v160, v126 offset:3456
	v_mul_f32_e32 v172, 0xbfb8aa3b, v96
	v_mul_f32_e32 v173, 0xbfb8aa3b, v97
	v_mul_f32_e32 v174, 0xbfb8aa3b, v98
	v_mul_f32_e32 v175, 0xbfb8aa3b, v99
	v_exp_f32_e32 v172, v172
	v_exp_f32_e32 v173, v173
	v_exp_f32_e32 v174, v174
	v_exp_f32_e32 v175, v175
	v_add_f32_e32 v172, 1.0, v172
	v_add_f32_e32 v173, 1.0, v173
	v_add_f32_e32 v174, 1.0, v174
	v_add_f32_e32 v175, 1.0, v175
	v_rcp_f32_e32 v172, v172
	v_rcp_f32_e32 v173, v173
	v_rcp_f32_e32 v174, v174
	v_rcp_f32_e32 v175, v175
	v_mul_f32_e32 v96, v96, v172
	v_mul_f32_e32 v97, v97, v173
	v_mul_f32_e32 v98, v98, v174
	v_mul_f32_e32 v99, v99, v175
	v_cvt_pk_bf16_f32 v96, v96, v97
	v_cvt_pk_bf16_f32 v98, v98, v99
	ds_write_b16 v161, v96 offset:0
	ds_write_b16_d16_hi v161, v96 offset:128
	ds_write_b16 v161, v98 offset:256
	ds_write_b16_d16_hi v161, v98 offset:384
	v_mul_f32_e32 v172, 0xbfb8aa3b, v100
	v_mul_f32_e32 v173, 0xbfb8aa3b, v101
	v_mul_f32_e32 v174, 0xbfb8aa3b, v102
	v_mul_f32_e32 v175, 0xbfb8aa3b, v103
	v_exp_f32_e32 v172, v172
	v_exp_f32_e32 v173, v173
	v_exp_f32_e32 v174, v174
	v_exp_f32_e32 v175, v175
	v_add_f32_e32 v172, 1.0, v172
	v_add_f32_e32 v173, 1.0, v173
	v_add_f32_e32 v174, 1.0, v174
	v_add_f32_e32 v175, 1.0, v175
	v_rcp_f32_e32 v172, v172
	v_rcp_f32_e32 v173, v173
	v_rcp_f32_e32 v174, v174
	v_rcp_f32_e32 v175, v175
	v_mul_f32_e32 v100, v100, v172
	v_mul_f32_e32 v101, v101, v173
	v_mul_f32_e32 v102, v102, v174
	v_mul_f32_e32 v103, v103, v175
	v_cvt_pk_bf16_f32 v100, v100, v101
	v_cvt_pk_bf16_f32 v102, v102, v103
	ds_write_b16 v161, v100 offset:1024
	ds_write_b16_d16_hi v161, v100 offset:1152
	ds_write_b16 v161, v102 offset:1280
	ds_write_b16_d16_hi v161, v102 offset:1408
	v_mul_f32_e32 v172, 0xbfb8aa3b, v104
	v_mul_f32_e32 v173, 0xbfb8aa3b, v105
	v_mul_f32_e32 v174, 0xbfb8aa3b, v106
	v_mul_f32_e32 v175, 0xbfb8aa3b, v107
	v_exp_f32_e32 v172, v172
	v_exp_f32_e32 v173, v173
	v_exp_f32_e32 v174, v174
	v_exp_f32_e32 v175, v175
	v_add_f32_e32 v172, 1.0, v172
	v_add_f32_e32 v173, 1.0, v173
	v_add_f32_e32 v174, 1.0, v174
	v_add_f32_e32 v175, 1.0, v175
	v_rcp_f32_e32 v172, v172
	v_rcp_f32_e32 v173, v173
	v_rcp_f32_e32 v174, v174
	v_rcp_f32_e32 v175, v175
	v_mul_f32_e32 v104, v104, v172
	v_mul_f32_e32 v105, v105, v173
	v_mul_f32_e32 v106, v106, v174
	v_mul_f32_e32 v107, v107, v175
	v_cvt_pk_bf16_f32 v104, v104, v105
	v_cvt_pk_bf16_f32 v106, v106, v107
	ds_write_b16 v161, v104 offset:2048
	ds_write_b16_d16_hi v161, v104 offset:2176
	ds_write_b16 v161, v106 offset:2304
	ds_write_b16_d16_hi v161, v106 offset:2432
	v_mul_f32_e32 v172, 0xbfb8aa3b, v108
	v_mul_f32_e32 v173, 0xbfb8aa3b, v109
	v_mul_f32_e32 v174, 0xbfb8aa3b, v110
	v_mul_f32_e32 v175, 0xbfb8aa3b, v111
	v_exp_f32_e32 v172, v172
	v_exp_f32_e32 v173, v173
	v_exp_f32_e32 v174, v174
	v_exp_f32_e32 v175, v175
	v_add_f32_e32 v172, 1.0, v172
	v_add_f32_e32 v173, 1.0, v173
	v_add_f32_e32 v174, 1.0, v174
	v_add_f32_e32 v175, 1.0, v175
	v_rcp_f32_e32 v172, v172
	v_rcp_f32_e32 v173, v173
	v_rcp_f32_e32 v174, v174
	v_rcp_f32_e32 v175, v175
	v_mul_f32_e32 v108, v108, v172
	v_mul_f32_e32 v109, v109, v173
	v_mul_f32_e32 v110, v110, v174
	v_mul_f32_e32 v111, v111, v175
	v_cvt_pk_bf16_f32 v108, v108, v109
	v_cvt_pk_bf16_f32 v110, v110, v111
	ds_write_b16 v161, v108 offset:3072
	ds_write_b16_d16_hi v161, v108 offset:3200
	ds_write_b16 v161, v110 offset:3328
	ds_write_b16_d16_hi v161, v110 offset:3456
	v_mul_f32_e32 v172, 0xbfb8aa3b, v80
	v_mul_f32_e32 v173, 0xbfb8aa3b, v81
	v_mul_f32_e32 v174, 0xbfb8aa3b, v82
	v_mul_f32_e32 v175, 0xbfb8aa3b, v83
	v_exp_f32_e32 v172, v172
	v_exp_f32_e32 v173, v173
	v_exp_f32_e32 v174, v174
	v_exp_f32_e32 v175, v175
	v_add_f32_e32 v172, 1.0, v172
	v_add_f32_e32 v173, 1.0, v173
	v_add_f32_e32 v174, 1.0, v174
	v_add_f32_e32 v175, 1.0, v175
	v_rcp_f32_e32 v172, v172
	v_rcp_f32_e32 v173, v173
	v_rcp_f32_e32 v174, v174
	v_rcp_f32_e32 v175, v175
	v_mul_f32_e32 v80, v80, v172
	v_mul_f32_e32 v81, v81, v173
	v_mul_f32_e32 v82, v82, v174
	v_mul_f32_e32 v83, v83, v175
	v_cvt_pk_bf16_f32 v80, v80, v81
	v_cvt_pk_bf16_f32 v82, v82, v83
	ds_write_b16 v160, v80 offset:4096
	ds_write_b16_d16_hi v160, v80 offset:4224
	ds_write_b16 v160, v82 offset:4352
	ds_write_b16_d16_hi v160, v82 offset:4480
	v_mul_f32_e32 v172, 0xbfb8aa3b, v84
	v_mul_f32_e32 v173, 0xbfb8aa3b, v85
	v_mul_f32_e32 v174, 0xbfb8aa3b, v86
	v_mul_f32_e32 v175, 0xbfb8aa3b, v87
	v_exp_f32_e32 v172, v172
	v_exp_f32_e32 v173, v173
	v_exp_f32_e32 v174, v174
	v_exp_f32_e32 v175, v175
	v_add_f32_e32 v172, 1.0, v172
	v_add_f32_e32 v173, 1.0, v173
	v_add_f32_e32 v174, 1.0, v174
	v_add_f32_e32 v175, 1.0, v175
	v_rcp_f32_e32 v172, v172
	v_rcp_f32_e32 v173, v173
	v_rcp_f32_e32 v174, v174
	v_rcp_f32_e32 v175, v175
	v_mul_f32_e32 v84, v84, v172
	v_mul_f32_e32 v85, v85, v173
	v_mul_f32_e32 v86, v86, v174
	v_mul_f32_e32 v87, v87, v175
	v_cvt_pk_bf16_f32 v84, v84, v85
	v_cvt_pk_bf16_f32 v86, v86, v87
	ds_write_b16 v160, v84 offset:5120
	ds_write_b16_d16_hi v160, v84 offset:5248
	ds_write_b16 v160, v86 offset:5376
	ds_write_b16_d16_hi v160, v86 offset:5504
	v_mul_f32_e32 v172, 0xbfb8aa3b, v88
	v_mul_f32_e32 v173, 0xbfb8aa3b, v89
	v_mul_f32_e32 v174, 0xbfb8aa3b, v90
	v_mul_f32_e32 v175, 0xbfb8aa3b, v91
	v_exp_f32_e32 v172, v172
	v_exp_f32_e32 v173, v173
	v_exp_f32_e32 v174, v174
	v_exp_f32_e32 v175, v175
	v_add_f32_e32 v172, 1.0, v172
	v_add_f32_e32 v173, 1.0, v173
	v_add_f32_e32 v174, 1.0, v174
	v_add_f32_e32 v175, 1.0, v175
	v_rcp_f32_e32 v172, v172
	v_rcp_f32_e32 v173, v173
	v_rcp_f32_e32 v174, v174
	v_rcp_f32_e32 v175, v175
	v_mul_f32_e32 v88, v88, v172
	v_mul_f32_e32 v89, v89, v173
	v_mul_f32_e32 v90, v90, v174
	v_mul_f32_e32 v91, v91, v175
	v_cvt_pk_bf16_f32 v88, v88, v89
	v_cvt_pk_bf16_f32 v90, v90, v91
	ds_write_b16 v160, v88 offset:6144
	ds_write_b16_d16_hi v160, v88 offset:6272
	ds_write_b16 v160, v90 offset:6400
	ds_write_b16_d16_hi v160, v90 offset:6528
	v_mul_f32_e32 v172, 0xbfb8aa3b, v92
	v_mul_f32_e32 v173, 0xbfb8aa3b, v93
	v_mul_f32_e32 v174, 0xbfb8aa3b, v94
	v_mul_f32_e32 v175, 0xbfb8aa3b, v95
	v_exp_f32_e32 v172, v172
	v_exp_f32_e32 v173, v173
	v_exp_f32_e32 v174, v174
	v_exp_f32_e32 v175, v175
	v_add_f32_e32 v172, 1.0, v172
	v_add_f32_e32 v173, 1.0, v173
	v_add_f32_e32 v174, 1.0, v174
	v_add_f32_e32 v175, 1.0, v175
	v_rcp_f32_e32 v172, v172
	v_rcp_f32_e32 v173, v173
	v_rcp_f32_e32 v174, v174
	v_rcp_f32_e32 v175, v175
	v_mul_f32_e32 v92, v92, v172
	v_mul_f32_e32 v93, v93, v173
	v_mul_f32_e32 v94, v94, v174
	v_mul_f32_e32 v95, v95, v175
	v_cvt_pk_bf16_f32 v92, v92, v93
	v_cvt_pk_bf16_f32 v94, v94, v95
	ds_write_b16 v160, v92 offset:7168
	ds_write_b16_d16_hi v160, v92 offset:7296
	ds_write_b16 v160, v94 offset:7424
	ds_write_b16_d16_hi v160, v94 offset:7552
	v_mul_f32_e32 v172, 0xbfb8aa3b, v64
	v_mul_f32_e32 v173, 0xbfb8aa3b, v65
	v_mul_f32_e32 v174, 0xbfb8aa3b, v66
	v_mul_f32_e32 v175, 0xbfb8aa3b, v67
	v_exp_f32_e32 v172, v172
	v_exp_f32_e32 v173, v173
	v_exp_f32_e32 v174, v174
	v_exp_f32_e32 v175, v175
	v_add_f32_e32 v172, 1.0, v172
	v_add_f32_e32 v173, 1.0, v173
	v_add_f32_e32 v174, 1.0, v174
	v_add_f32_e32 v175, 1.0, v175
	v_rcp_f32_e32 v172, v172
	v_rcp_f32_e32 v173, v173
	v_rcp_f32_e32 v174, v174
	v_rcp_f32_e32 v175, v175
	v_mul_f32_e32 v64, v64, v172
	v_mul_f32_e32 v65, v65, v173
	v_mul_f32_e32 v66, v66, v174
	v_mul_f32_e32 v67, v67, v175
	v_cvt_pk_bf16_f32 v64, v64, v65
	v_cvt_pk_bf16_f32 v66, v66, v67
	ds_write_b16 v161, v64 offset:4096
	ds_write_b16_d16_hi v161, v64 offset:4224
	ds_write_b16 v161, v66 offset:4352
	ds_write_b16_d16_hi v161, v66 offset:4480
	v_mul_f32_e32 v172, 0xbfb8aa3b, v68
	v_mul_f32_e32 v173, 0xbfb8aa3b, v69
	v_mul_f32_e32 v174, 0xbfb8aa3b, v70
	v_mul_f32_e32 v175, 0xbfb8aa3b, v71
	v_exp_f32_e32 v172, v172
	v_exp_f32_e32 v173, v173
	v_exp_f32_e32 v174, v174
	v_exp_f32_e32 v175, v175
	v_add_f32_e32 v172, 1.0, v172
	v_add_f32_e32 v173, 1.0, v173
	v_add_f32_e32 v174, 1.0, v174
	v_add_f32_e32 v175, 1.0, v175
	v_rcp_f32_e32 v172, v172
	v_rcp_f32_e32 v173, v173
	v_rcp_f32_e32 v174, v174
	v_rcp_f32_e32 v175, v175
	v_mul_f32_e32 v68, v68, v172
	v_mul_f32_e32 v69, v69, v173
	v_mul_f32_e32 v70, v70, v174
	v_mul_f32_e32 v71, v71, v175
	v_cvt_pk_bf16_f32 v68, v68, v69
	v_cvt_pk_bf16_f32 v70, v70, v71
	ds_write_b16 v161, v68 offset:5120
	ds_write_b16_d16_hi v161, v68 offset:5248
	ds_write_b16 v161, v70 offset:5376
	ds_write_b16_d16_hi v161, v70 offset:5504
	v_mul_f32_e32 v172, 0xbfb8aa3b, v72
	v_mul_f32_e32 v173, 0xbfb8aa3b, v73
	v_mul_f32_e32 v174, 0xbfb8aa3b, v74
	v_mul_f32_e32 v175, 0xbfb8aa3b, v75
	v_exp_f32_e32 v172, v172
	v_exp_f32_e32 v173, v173
	v_exp_f32_e32 v174, v174
	v_exp_f32_e32 v175, v175
	v_add_f32_e32 v172, 1.0, v172
	v_add_f32_e32 v173, 1.0, v173
	v_add_f32_e32 v174, 1.0, v174
	v_add_f32_e32 v175, 1.0, v175
	v_rcp_f32_e32 v172, v172
	v_rcp_f32_e32 v173, v173
	v_rcp_f32_e32 v174, v174
	v_rcp_f32_e32 v175, v175
	v_mul_f32_e32 v72, v72, v172
	v_mul_f32_e32 v73, v73, v173
	v_mul_f32_e32 v74, v74, v174
	v_mul_f32_e32 v75, v75, v175
	v_cvt_pk_bf16_f32 v72, v72, v73
	v_cvt_pk_bf16_f32 v74, v74, v75
	ds_write_b16 v161, v72 offset:6144
	ds_write_b16_d16_hi v161, v72 offset:6272
	ds_write_b16 v161, v74 offset:6400
	ds_write_b16_d16_hi v161, v74 offset:6528
	v_mul_f32_e32 v172, 0xbfb8aa3b, v76
	v_mul_f32_e32 v173, 0xbfb8aa3b, v77
	v_mul_f32_e32 v174, 0xbfb8aa3b, v78
	v_mul_f32_e32 v175, 0xbfb8aa3b, v79
	v_exp_f32_e32 v172, v172
	v_exp_f32_e32 v173, v173
	v_exp_f32_e32 v174, v174
	v_exp_f32_e32 v175, v175
	v_add_f32_e32 v172, 1.0, v172
	v_add_f32_e32 v173, 1.0, v173
	v_add_f32_e32 v174, 1.0, v174
	v_add_f32_e32 v175, 1.0, v175
	v_rcp_f32_e32 v172, v172
	v_rcp_f32_e32 v173, v173
	v_rcp_f32_e32 v174, v174
	v_rcp_f32_e32 v175, v175
	v_mul_f32_e32 v76, v76, v172
	v_mul_f32_e32 v77, v77, v173
	v_mul_f32_e32 v78, v78, v174
	v_mul_f32_e32 v79, v79, v175
	v_cvt_pk_bf16_f32 v76, v76, v77
	v_cvt_pk_bf16_f32 v78, v78, v79
	ds_write_b16 v161, v76 offset:7168
	ds_write_b16_d16_hi v161, v76 offset:7296
	ds_write_b16 v161, v78 offset:7424
	ds_write_b16_d16_hi v161, v78 offset:7552
	v_mul_f32_e32 v172, 0xbfb8aa3b, v48
	v_mul_f32_e32 v173, 0xbfb8aa3b, v49
	v_mul_f32_e32 v174, 0xbfb8aa3b, v50
	v_mul_f32_e32 v175, 0xbfb8aa3b, v51
	v_exp_f32_e32 v172, v172
	v_exp_f32_e32 v173, v173
	v_exp_f32_e32 v174, v174
	v_exp_f32_e32 v175, v175
	v_add_f32_e32 v172, 1.0, v172
	v_add_f32_e32 v173, 1.0, v173
	v_add_f32_e32 v174, 1.0, v174
	v_add_f32_e32 v175, 1.0, v175
	v_rcp_f32_e32 v172, v172
	v_rcp_f32_e32 v173, v173
	v_rcp_f32_e32 v174, v174
	v_rcp_f32_e32 v175, v175
	v_mul_f32_e32 v48, v48, v172
	v_mul_f32_e32 v49, v49, v173
	v_mul_f32_e32 v50, v50, v174
	v_mul_f32_e32 v51, v51, v175
	v_cvt_pk_bf16_f32 v48, v48, v49
	v_cvt_pk_bf16_f32 v50, v50, v51
	ds_write_b16 v160, v48 offset:8192
	ds_write_b16_d16_hi v160, v48 offset:8320
	ds_write_b16 v160, v50 offset:8448
	ds_write_b16_d16_hi v160, v50 offset:8576
	v_mul_f32_e32 v172, 0xbfb8aa3b, v52
	v_mul_f32_e32 v173, 0xbfb8aa3b, v53
	v_mul_f32_e32 v174, 0xbfb8aa3b, v54
	v_mul_f32_e32 v175, 0xbfb8aa3b, v55
	v_exp_f32_e32 v172, v172
	v_exp_f32_e32 v173, v173
	v_exp_f32_e32 v174, v174
	v_exp_f32_e32 v175, v175
	v_add_f32_e32 v172, 1.0, v172
	v_add_f32_e32 v173, 1.0, v173
	v_add_f32_e32 v174, 1.0, v174
	v_add_f32_e32 v175, 1.0, v175
	v_rcp_f32_e32 v172, v172
	v_rcp_f32_e32 v173, v173
	v_rcp_f32_e32 v174, v174
	v_rcp_f32_e32 v175, v175
	v_mul_f32_e32 v52, v52, v172
	v_mul_f32_e32 v53, v53, v173
	v_mul_f32_e32 v54, v54, v174
	v_mul_f32_e32 v55, v55, v175
	v_cvt_pk_bf16_f32 v52, v52, v53
	v_cvt_pk_bf16_f32 v54, v54, v55
	ds_write_b16 v160, v52 offset:9216
	ds_write_b16_d16_hi v160, v52 offset:9344
	ds_write_b16 v160, v54 offset:9472
	ds_write_b16_d16_hi v160, v54 offset:9600
	v_mul_f32_e32 v172, 0xbfb8aa3b, v56
	v_mul_f32_e32 v173, 0xbfb8aa3b, v57
	v_mul_f32_e32 v174, 0xbfb8aa3b, v58
	v_mul_f32_e32 v175, 0xbfb8aa3b, v59
	v_exp_f32_e32 v172, v172
	v_exp_f32_e32 v173, v173
	v_exp_f32_e32 v174, v174
	v_exp_f32_e32 v175, v175
	v_add_f32_e32 v172, 1.0, v172
	v_add_f32_e32 v173, 1.0, v173
	v_add_f32_e32 v174, 1.0, v174
	v_add_f32_e32 v175, 1.0, v175
	v_rcp_f32_e32 v172, v172
	v_rcp_f32_e32 v173, v173
	v_rcp_f32_e32 v174, v174
	v_rcp_f32_e32 v175, v175
	v_mul_f32_e32 v56, v56, v172
	v_mul_f32_e32 v57, v57, v173
	v_mul_f32_e32 v58, v58, v174
	v_mul_f32_e32 v59, v59, v175
	v_cvt_pk_bf16_f32 v56, v56, v57
	v_cvt_pk_bf16_f32 v58, v58, v59
	ds_write_b16 v160, v56 offset:10240
	ds_write_b16_d16_hi v160, v56 offset:10368
	ds_write_b16 v160, v58 offset:10496
	ds_write_b16_d16_hi v160, v58 offset:10624
	v_mul_f32_e32 v172, 0xbfb8aa3b, v60
	v_mul_f32_e32 v173, 0xbfb8aa3b, v61
	v_mul_f32_e32 v174, 0xbfb8aa3b, v62
	v_mul_f32_e32 v175, 0xbfb8aa3b, v63
	v_exp_f32_e32 v172, v172
	v_exp_f32_e32 v173, v173
	v_exp_f32_e32 v174, v174
	v_exp_f32_e32 v175, v175
	v_add_f32_e32 v172, 1.0, v172
	v_add_f32_e32 v173, 1.0, v173
	v_add_f32_e32 v174, 1.0, v174
	v_add_f32_e32 v175, 1.0, v175
	v_rcp_f32_e32 v172, v172
	v_rcp_f32_e32 v173, v173
	v_rcp_f32_e32 v174, v174
	v_rcp_f32_e32 v175, v175
	v_mul_f32_e32 v60, v60, v172
	v_mul_f32_e32 v61, v61, v173
	v_mul_f32_e32 v62, v62, v174
	v_mul_f32_e32 v63, v63, v175
	v_cvt_pk_bf16_f32 v60, v60, v61
	v_cvt_pk_bf16_f32 v62, v62, v63
	ds_write_b16 v160, v60 offset:11264
	ds_write_b16_d16_hi v160, v60 offset:11392
	ds_write_b16 v160, v62 offset:11520
	ds_write_b16_d16_hi v160, v62 offset:11648
	v_mul_f32_e32 v172, 0xbfb8aa3b, v32
	v_mul_f32_e32 v173, 0xbfb8aa3b, v33
	v_mul_f32_e32 v174, 0xbfb8aa3b, v34
	v_mul_f32_e32 v175, 0xbfb8aa3b, v35
	v_exp_f32_e32 v172, v172
	v_exp_f32_e32 v173, v173
	v_exp_f32_e32 v174, v174
	v_exp_f32_e32 v175, v175
	v_add_f32_e32 v172, 1.0, v172
	v_add_f32_e32 v173, 1.0, v173
	v_add_f32_e32 v174, 1.0, v174
	v_add_f32_e32 v175, 1.0, v175
	v_rcp_f32_e32 v172, v172
	v_rcp_f32_e32 v173, v173
	v_rcp_f32_e32 v174, v174
	v_rcp_f32_e32 v175, v175
	v_mul_f32_e32 v32, v32, v172
	v_mul_f32_e32 v33, v33, v173
	v_mul_f32_e32 v34, v34, v174
	v_mul_f32_e32 v35, v35, v175
	v_cvt_pk_bf16_f32 v32, v32, v33
	v_cvt_pk_bf16_f32 v34, v34, v35
	ds_write_b16 v161, v32 offset:8192
	ds_write_b16_d16_hi v161, v32 offset:8320
	ds_write_b16 v161, v34 offset:8448
	ds_write_b16_d16_hi v161, v34 offset:8576
	v_mul_f32_e32 v172, 0xbfb8aa3b, v36
	v_mul_f32_e32 v173, 0xbfb8aa3b, v37
	v_mul_f32_e32 v174, 0xbfb8aa3b, v38
	v_mul_f32_e32 v175, 0xbfb8aa3b, v39
	v_exp_f32_e32 v172, v172
	v_exp_f32_e32 v173, v173
	v_exp_f32_e32 v174, v174
	v_exp_f32_e32 v175, v175
	v_add_f32_e32 v172, 1.0, v172
	v_add_f32_e32 v173, 1.0, v173
	v_add_f32_e32 v174, 1.0, v174
	v_add_f32_e32 v175, 1.0, v175
	v_rcp_f32_e32 v172, v172
	v_rcp_f32_e32 v173, v173
	v_rcp_f32_e32 v174, v174
	v_rcp_f32_e32 v175, v175
	v_mul_f32_e32 v36, v36, v172
	v_mul_f32_e32 v37, v37, v173
	v_mul_f32_e32 v38, v38, v174
	v_mul_f32_e32 v39, v39, v175
	v_cvt_pk_bf16_f32 v36, v36, v37
	v_cvt_pk_bf16_f32 v38, v38, v39
	ds_write_b16 v161, v36 offset:9216
	ds_write_b16_d16_hi v161, v36 offset:9344
	ds_write_b16 v161, v38 offset:9472
	ds_write_b16_d16_hi v161, v38 offset:9600
	v_mul_f32_e32 v172, 0xbfb8aa3b, v40
	v_mul_f32_e32 v173, 0xbfb8aa3b, v41
	v_mul_f32_e32 v174, 0xbfb8aa3b, v42
	v_mul_f32_e32 v175, 0xbfb8aa3b, v43
	v_exp_f32_e32 v172, v172
	v_exp_f32_e32 v173, v173
	v_exp_f32_e32 v174, v174
	v_exp_f32_e32 v175, v175
	v_add_f32_e32 v172, 1.0, v172
	v_add_f32_e32 v173, 1.0, v173
	v_add_f32_e32 v174, 1.0, v174
	v_add_f32_e32 v175, 1.0, v175
	v_rcp_f32_e32 v172, v172
	v_rcp_f32_e32 v173, v173
	v_rcp_f32_e32 v174, v174
	v_rcp_f32_e32 v175, v175
	v_mul_f32_e32 v40, v40, v172
	v_mul_f32_e32 v41, v41, v173
	v_mul_f32_e32 v42, v42, v174
	v_mul_f32_e32 v43, v43, v175
	v_cvt_pk_bf16_f32 v40, v40, v41
	v_cvt_pk_bf16_f32 v42, v42, v43
	ds_write_b16 v161, v40 offset:10240
	ds_write_b16_d16_hi v161, v40 offset:10368
	ds_write_b16 v161, v42 offset:10496
	ds_write_b16_d16_hi v161, v42 offset:10624
	v_mul_f32_e32 v172, 0xbfb8aa3b, v44
	v_mul_f32_e32 v173, 0xbfb8aa3b, v45
	v_mul_f32_e32 v174, 0xbfb8aa3b, v46
	v_mul_f32_e32 v175, 0xbfb8aa3b, v47
	v_exp_f32_e32 v172, v172
	v_exp_f32_e32 v173, v173
	v_exp_f32_e32 v174, v174
	v_exp_f32_e32 v175, v175
	v_add_f32_e32 v172, 1.0, v172
	v_add_f32_e32 v173, 1.0, v173
	v_add_f32_e32 v174, 1.0, v174
	v_add_f32_e32 v175, 1.0, v175
	v_rcp_f32_e32 v172, v172
	v_rcp_f32_e32 v173, v173
	v_rcp_f32_e32 v174, v174
	v_rcp_f32_e32 v175, v175
	v_mul_f32_e32 v44, v44, v172
	v_mul_f32_e32 v45, v45, v173
	v_mul_f32_e32 v46, v46, v174
	v_mul_f32_e32 v47, v47, v175
	v_cvt_pk_bf16_f32 v44, v44, v45
	v_cvt_pk_bf16_f32 v46, v46, v47
	ds_write_b16 v161, v44 offset:11264
	ds_write_b16_d16_hi v161, v44 offset:11392
	ds_write_b16 v161, v46 offset:11520
	ds_write_b16_d16_hi v161, v46 offset:11648
	v_mul_f32_e32 v172, 0xbfb8aa3b, v16
	v_mul_f32_e32 v173, 0xbfb8aa3b, v17
	v_mul_f32_e32 v174, 0xbfb8aa3b, v18
	v_mul_f32_e32 v175, 0xbfb8aa3b, v19
	v_exp_f32_e32 v172, v172
	v_exp_f32_e32 v173, v173
	v_exp_f32_e32 v174, v174
	v_exp_f32_e32 v175, v175
	v_add_f32_e32 v172, 1.0, v172
	v_add_f32_e32 v173, 1.0, v173
	v_add_f32_e32 v174, 1.0, v174
	v_add_f32_e32 v175, 1.0, v175
	v_rcp_f32_e32 v172, v172
	v_rcp_f32_e32 v173, v173
	v_rcp_f32_e32 v174, v174
	v_rcp_f32_e32 v175, v175
	v_mul_f32_e32 v16, v16, v172
	v_mul_f32_e32 v17, v17, v173
	v_mul_f32_e32 v18, v18, v174
	v_mul_f32_e32 v19, v19, v175
	v_cvt_pk_bf16_f32 v16, v16, v17
	v_cvt_pk_bf16_f32 v18, v18, v19
	ds_write_b16 v160, v16 offset:12288
	ds_write_b16_d16_hi v160, v16 offset:12416
	ds_write_b16 v160, v18 offset:12544
	ds_write_b16_d16_hi v160, v18 offset:12672
	v_mul_f32_e32 v172, 0xbfb8aa3b, v20
	v_mul_f32_e32 v173, 0xbfb8aa3b, v21
	v_mul_f32_e32 v174, 0xbfb8aa3b, v22
	v_mul_f32_e32 v175, 0xbfb8aa3b, v23
	v_exp_f32_e32 v172, v172
	v_exp_f32_e32 v173, v173
	v_exp_f32_e32 v174, v174
	v_exp_f32_e32 v175, v175
	v_add_f32_e32 v172, 1.0, v172
	v_add_f32_e32 v173, 1.0, v173
	v_add_f32_e32 v174, 1.0, v174
	v_add_f32_e32 v175, 1.0, v175
	v_rcp_f32_e32 v172, v172
	v_rcp_f32_e32 v173, v173
	v_rcp_f32_e32 v174, v174
	v_rcp_f32_e32 v175, v175
	v_mul_f32_e32 v20, v20, v172
	v_mul_f32_e32 v21, v21, v173
	v_mul_f32_e32 v22, v22, v174
	v_mul_f32_e32 v23, v23, v175
	v_cvt_pk_bf16_f32 v20, v20, v21
	v_cvt_pk_bf16_f32 v22, v22, v23
	ds_write_b16 v160, v20 offset:13312
	ds_write_b16_d16_hi v160, v20 offset:13440
	ds_write_b16 v160, v22 offset:13568
	ds_write_b16_d16_hi v160, v22 offset:13696
	v_mul_f32_e32 v172, 0xbfb8aa3b, v24
	v_mul_f32_e32 v173, 0xbfb8aa3b, v25
	v_mul_f32_e32 v174, 0xbfb8aa3b, v26
	v_mul_f32_e32 v175, 0xbfb8aa3b, v27
	v_exp_f32_e32 v172, v172
	v_exp_f32_e32 v173, v173
	v_exp_f32_e32 v174, v174
	v_exp_f32_e32 v175, v175
	v_add_f32_e32 v172, 1.0, v172
	v_add_f32_e32 v173, 1.0, v173
	v_add_f32_e32 v174, 1.0, v174
	v_add_f32_e32 v175, 1.0, v175
	v_rcp_f32_e32 v172, v172
	v_rcp_f32_e32 v173, v173
	v_rcp_f32_e32 v174, v174
	v_rcp_f32_e32 v175, v175
	v_mul_f32_e32 v24, v24, v172
	v_mul_f32_e32 v25, v25, v173
	v_mul_f32_e32 v26, v26, v174
	v_mul_f32_e32 v27, v27, v175
	v_cvt_pk_bf16_f32 v24, v24, v25
	v_cvt_pk_bf16_f32 v26, v26, v27
	ds_write_b16 v160, v24 offset:14336
	ds_write_b16_d16_hi v160, v24 offset:14464
	ds_write_b16 v160, v26 offset:14592
	ds_write_b16_d16_hi v160, v26 offset:14720
	v_mul_f32_e32 v172, 0xbfb8aa3b, v28
	v_mul_f32_e32 v173, 0xbfb8aa3b, v29
	v_mul_f32_e32 v174, 0xbfb8aa3b, v30
	v_mul_f32_e32 v175, 0xbfb8aa3b, v31
	v_exp_f32_e32 v172, v172
	v_exp_f32_e32 v173, v173
	v_exp_f32_e32 v174, v174
	v_exp_f32_e32 v175, v175
	v_add_f32_e32 v172, 1.0, v172
	v_add_f32_e32 v173, 1.0, v173
	v_add_f32_e32 v174, 1.0, v174
	v_add_f32_e32 v175, 1.0, v175
	v_rcp_f32_e32 v172, v172
	v_rcp_f32_e32 v173, v173
	v_rcp_f32_e32 v174, v174
	v_rcp_f32_e32 v175, v175
	v_mul_f32_e32 v28, v28, v172
	v_mul_f32_e32 v29, v29, v173
	v_mul_f32_e32 v30, v30, v174
	v_mul_f32_e32 v31, v31, v175
	v_cvt_pk_bf16_f32 v28, v28, v29
	v_cvt_pk_bf16_f32 v30, v30, v31
	ds_write_b16 v160, v28 offset:15360
	ds_write_b16_d16_hi v160, v28 offset:15488
	ds_write_b16 v160, v30 offset:15616
	ds_write_b16_d16_hi v160, v30 offset:15744
	v_mul_f32_e32 v172, 0xbfb8aa3b, v0
	v_mul_f32_e32 v173, 0xbfb8aa3b, v1
	v_mul_f32_e32 v174, 0xbfb8aa3b, v2
	v_mul_f32_e32 v175, 0xbfb8aa3b, v3
	v_exp_f32_e32 v172, v172
	v_exp_f32_e32 v173, v173
	v_exp_f32_e32 v174, v174
	v_exp_f32_e32 v175, v175
	v_add_f32_e32 v172, 1.0, v172
	v_add_f32_e32 v173, 1.0, v173
	v_add_f32_e32 v174, 1.0, v174
	v_add_f32_e32 v175, 1.0, v175
	v_rcp_f32_e32 v172, v172
	v_rcp_f32_e32 v173, v173
	v_rcp_f32_e32 v174, v174
	v_rcp_f32_e32 v175, v175
	v_mul_f32_e32 v0, v0, v172
	v_mul_f32_e32 v1, v1, v173
	v_mul_f32_e32 v2, v2, v174
	v_mul_f32_e32 v3, v3, v175
	v_cvt_pk_bf16_f32 v0, v0, v1
	v_cvt_pk_bf16_f32 v2, v2, v3
	ds_write_b16 v161, v0 offset:12288
	ds_write_b16_d16_hi v161, v0 offset:12416
	ds_write_b16 v161, v2 offset:12544
	ds_write_b16_d16_hi v161, v2 offset:12672
	v_mul_f32_e32 v172, 0xbfb8aa3b, v4
	v_mul_f32_e32 v173, 0xbfb8aa3b, v5
	v_mul_f32_e32 v174, 0xbfb8aa3b, v6
	v_mul_f32_e32 v175, 0xbfb8aa3b, v7
	v_exp_f32_e32 v172, v172
	v_exp_f32_e32 v173, v173
	v_exp_f32_e32 v174, v174
	v_exp_f32_e32 v175, v175
	v_add_f32_e32 v172, 1.0, v172
	v_add_f32_e32 v173, 1.0, v173
	v_add_f32_e32 v174, 1.0, v174
	v_add_f32_e32 v175, 1.0, v175
	v_rcp_f32_e32 v172, v172
	v_rcp_f32_e32 v173, v173
	v_rcp_f32_e32 v174, v174
	v_rcp_f32_e32 v175, v175
	v_mul_f32_e32 v4, v4, v172
	v_mul_f32_e32 v5, v5, v173
	v_mul_f32_e32 v6, v6, v174
	v_mul_f32_e32 v7, v7, v175
	v_cvt_pk_bf16_f32 v4, v4, v5
	v_cvt_pk_bf16_f32 v6, v6, v7
	ds_write_b16 v161, v4 offset:13312
	ds_write_b16_d16_hi v161, v4 offset:13440
	ds_write_b16 v161, v6 offset:13568
	ds_write_b16_d16_hi v161, v6 offset:13696
	v_mul_f32_e32 v172, 0xbfb8aa3b, v8
	v_mul_f32_e32 v173, 0xbfb8aa3b, v9
	v_mul_f32_e32 v174, 0xbfb8aa3b, v10
	v_mul_f32_e32 v175, 0xbfb8aa3b, v11
	v_exp_f32_e32 v172, v172
	v_exp_f32_e32 v173, v173
	v_exp_f32_e32 v174, v174
	v_exp_f32_e32 v175, v175
	v_add_f32_e32 v172, 1.0, v172
	v_add_f32_e32 v173, 1.0, v173
	v_add_f32_e32 v174, 1.0, v174
	v_add_f32_e32 v175, 1.0, v175
	v_rcp_f32_e32 v172, v172
	v_rcp_f32_e32 v173, v173
	v_rcp_f32_e32 v174, v174
	v_rcp_f32_e32 v175, v175
	v_mul_f32_e32 v8, v8, v172
	v_mul_f32_e32 v9, v9, v173
	v_mul_f32_e32 v10, v10, v174
	v_mul_f32_e32 v11, v11, v175
	v_cvt_pk_bf16_f32 v8, v8, v9
	v_cvt_pk_bf16_f32 v10, v10, v11
	ds_write_b16 v161, v8 offset:14336
	ds_write_b16_d16_hi v161, v8 offset:14464
	ds_write_b16 v161, v10 offset:14592
	ds_write_b16_d16_hi v161, v10 offset:14720
	v_mul_f32_e32 v172, 0xbfb8aa3b, v12
	v_mul_f32_e32 v173, 0xbfb8aa3b, v13
	v_mul_f32_e32 v174, 0xbfb8aa3b, v14
	v_mul_f32_e32 v175, 0xbfb8aa3b, v15
	v_exp_f32_e32 v172, v172
	v_exp_f32_e32 v173, v173
	v_exp_f32_e32 v174, v174
	v_exp_f32_e32 v175, v175
	v_add_f32_e32 v172, 1.0, v172
	v_add_f32_e32 v173, 1.0, v173
	v_add_f32_e32 v174, 1.0, v174
	v_add_f32_e32 v175, 1.0, v175
	v_rcp_f32_e32 v172, v172
	v_rcp_f32_e32 v173, v173
	v_rcp_f32_e32 v174, v174
	v_rcp_f32_e32 v175, v175
	v_mul_f32_e32 v12, v12, v172
	v_mul_f32_e32 v13, v13, v173
	v_mul_f32_e32 v14, v14, v174
	v_mul_f32_e32 v15, v15, v175
	v_cvt_pk_bf16_f32 v12, v12, v13
	v_cvt_pk_bf16_f32 v14, v14, v15
	ds_write_b16 v161, v12 offset:15360
	ds_write_b16_d16_hi v161, v12 offset:15488
	ds_write_b16 v161, v14 offset:15616
	ds_write_b16_d16_hi v161, v14 offset:15744
	s_waitcnt lgkmcnt(0)
	ds_read_b128 v[128:131], v166 offset:0
	ds_read_b128 v[132:135], v166 offset:1024
	ds_read_b128 v[136:139], v166 offset:2048
	ds_read_b128 v[140:143], v166 offset:3072
	s_waitcnt lgkmcnt(3)
	global_store_dwordx4 v[170:171], v[128:131], off
	v_lshl_add_u64 v[170:171], v[170:171], 0, s[8:9]
	s_waitcnt lgkmcnt(2)
	global_store_dwordx4 v[170:171], v[132:135], off
	v_lshl_add_u64 v[170:171], v[170:171], 0, s[8:9]
	s_waitcnt lgkmcnt(1)
	global_store_dwordx4 v[170:171], v[136:139], off
	v_lshl_add_u64 v[170:171], v[170:171], 0, s[8:9]
	s_waitcnt lgkmcnt(0)
	global_store_dwordx4 v[170:171], v[140:143], off
	v_lshl_add_u64 v[170:171], v[170:171], 0, s[8:9]
	ds_read_b128 v[128:131], v166 offset:4096
	ds_read_b128 v[132:135], v166 offset:5120
	ds_read_b128 v[136:139], v166 offset:6144
	ds_read_b128 v[140:143], v166 offset:7168
	s_waitcnt lgkmcnt(3)
	global_store_dwordx4 v[170:171], v[128:131], off
	v_lshl_add_u64 v[170:171], v[170:171], 0, s[8:9]
	s_waitcnt lgkmcnt(2)
	global_store_dwordx4 v[170:171], v[132:135], off
	v_lshl_add_u64 v[170:171], v[170:171], 0, s[8:9]
	s_waitcnt lgkmcnt(1)
	global_store_dwordx4 v[170:171], v[136:139], off
	v_lshl_add_u64 v[170:171], v[170:171], 0, s[8:9]
	s_waitcnt lgkmcnt(0)
	global_store_dwordx4 v[170:171], v[140:143], off
	v_lshl_add_u64 v[170:171], v[170:171], 0, s[8:9]
	ds_read_b128 v[128:131], v166 offset:8192
	ds_read_b128 v[132:135], v166 offset:9216
	ds_read_b128 v[136:139], v166 offset:10240
	ds_read_b128 v[140:143], v166 offset:11264
	s_waitcnt lgkmcnt(3)
	global_store_dwordx4 v[170:171], v[128:131], off
	v_lshl_add_u64 v[170:171], v[170:171], 0, s[8:9]
	s_waitcnt lgkmcnt(2)
	global_store_dwordx4 v[170:171], v[132:135], off
	v_lshl_add_u64 v[170:171], v[170:171], 0, s[8:9]
	s_waitcnt lgkmcnt(1)
	global_store_dwordx4 v[170:171], v[136:139], off
	v_lshl_add_u64 v[170:171], v[170:171], 0, s[8:9]
	s_waitcnt lgkmcnt(0)
	global_store_dwordx4 v[170:171], v[140:143], off
	v_lshl_add_u64 v[170:171], v[170:171], 0, s[8:9]
	ds_read_b128 v[128:131], v166 offset:12288
	ds_read_b128 v[132:135], v166 offset:13312
	ds_read_b128 v[136:139], v166 offset:14336
	ds_read_b128 v[140:143], v166 offset:15360
	s_waitcnt lgkmcnt(3)
	global_store_dwordx4 v[170:171], v[128:131], off
	v_lshl_add_u64 v[170:171], v[170:171], 0, s[8:9]
	s_waitcnt lgkmcnt(2)
	global_store_dwordx4 v[170:171], v[132:135], off
	v_lshl_add_u64 v[170:171], v[170:171], 0, s[8:9]
	s_waitcnt lgkmcnt(1)
	global_store_dwordx4 v[170:171], v[136:139], off
	v_lshl_add_u64 v[170:171], v[170:171], 0, s[8:9]
	s_waitcnt lgkmcnt(0)
	global_store_dwordx4 v[170:171], v[140:143], off
	v_lshl_add_u64 v[170:171], v[170:171], 0, s[8:9]
.Lg8_skip:
	s_mov_b64 s[0:1], exec
